# a2 + diff attention K/V prefetch via scalar base + VGPR offset; FoX c2 negation deferred to the LDS store (no vmcnt(0) at prefetch)
# speedup vs baseline: 1.0256x; 1.0089x over previous
; #define A_GLOAD(KR, VR, CR, JT) { const int s1_ = (JT) * 64; KR = *(const u32x4*)(kp + (size_t)s1_ * ldk); \
;     _Pragma("unroll") for (int i_ = 0; i_ < DVT / 2; ++i_) VR[i_] = *(const u32x4*)(vp + (size_t)(64 * i_) * SEQ + s1_); \
;     if (FOX) { if (tid < 16) { f32x4 t_ = *(const f32x4*)(cbase + s1_ + tid * 4); CR[0] = -t_[0]; CR[1] = -t_[1]; CR[2] = -t_[2]; CR[3] = -t_[3]; } } }
; template <int DVT, bool FOX> ...
;     ...
;   int j = j_hi;
;   A_GLOAD(kr0, vr0, cr0, j);
;   if (j >= 1) A_GLOAD(kr1, vr1, cr1, j - 1);
.LBB0_198:
	s_or_b64 exec, exec, s[14:15]
	s_addk_i32 s4, 0x100
	s_ashr_i32 s87, s4, 6
	s_cmp_lt_i32 s87, 2
	s_cbranch_scc1 .LBB0_202
	s_sub_i32 s96, s12, 64
	s_lshl_b64 s[4:5], s[96:97], 11
	v_lshl_add_u64 v[12:13], v[118:119], 0, s[4:5]
	v_lshl_add_u64 v[14:15], s[96:97], 1, v[120:121]
	global_load_dwordx4 v[94:97], v[12:13], off
	global_load_dwordx4 v[102:105], v[14:15], off
	v_mov_b32_e32 v98, v1
	v_mov_b32_e32 v99, v1
	v_mov_b32_e32 v100, v1
	v_mov_b32_e32 v101, v1
	s_and_saveexec_b64 s[4:5], s[8:9]
	s_cbranch_execz .LBB0_201
	s_lshl_b64 s[12:13], s[96:97], 2
	s_add_u32 s12, s78, s12
	s_addc_u32 s13, s79, s13
	v_lshl_add_u64 v[12:13], v[6:7], 2, s[12:13]
	global_load_dwordx4 v[12:15], v[12:13], off
	s_waitcnt vmcnt(0)
	v_mov_b32_e32 v101, v15
	v_mov_b32_e32 v100, v14
	v_mov_b32_e32 v99, v13
	v_mov_b32_e32 v98, v12

; #define A_LSTORE(KR, VR, CR, STG) { char* kb_ = lds + (STG) * STAGE; char* vb_ = kb_ + 64 * LROW; char* cb_ = vb_ + VB; \
;     *(u32x4*)(kb_ + lrow * LROW + lch * 16) = KR; \
;     _Pragma("unroll") for (int i_ = 0; i_ < DVT / 2; ++i_) *(u32x4*)(vb_ + (lrow + 64 * i_) * LROW + lch * 16) = VR[i_]; \
;     if (FOX) { if (tid < 16) *(f32x4*)(cb_ + tid * 16) = CR; } }
; template <int DVT, bool FOX> ...
;     ...
;     A_LSTORE(kr1, vr1, cr1, 1);
.LBB0_213:
	v_xor_b32_e32 v98, 0x80000000, v98
	v_xor_b32_e32 v99, 0x80000000, v99
	v_xor_b32_e32 v100, 0x80000000, v100
	v_xor_b32_e32 v101, 0x80000000, v101
	ds_write_b128 v142, v[98:101] offset:37120

; #define A_LSTORE(KR, VR, CR, STG) { char* kb_ = lds + (STG) * STAGE; char* vb_ = kb_ + 64 * LROW; char* cb_ = vb_ + VB; \
;     *(u32x4*)(kb_ + lrow * LROW + lch * 16) = KR; \
;     _Pragma("unroll") for (int i_ = 0; i_ < DVT / 2; ++i_) *(u32x4*)(vb_ + (lrow + 64 * i_) * LROW + lch * 16) = VR[i_]; \
;     if (FOX) { if (tid < 16) *(f32x4*)(cb_ + tid * 16) = CR; } }
; template <int DVT, bool FOX> ...
;     ...
;     A_LSTORE(kr0, vr0, cr0, 0);
.LBB0_220:
	s_waitcnt vmcnt(1)
	ds_write_b128 v141, v[82:85]
	s_waitcnt vmcnt(0)
	ds_write_b128 v141, v[86:89] offset:9216
	s_and_saveexec_b64 s[88:89], s[8:9]
	s_cbranch_execz .LBB0_206
	v_xor_b32_e32 v90, 0x80000000, v90
	v_xor_b32_e32 v91, 0x80000000, v91
	v_xor_b32_e32 v92, 0x80000000, v92
	v_xor_b32_e32 v93, 0x80000000, v93
	ds_write_b128 v142, v[90:93] offset:18432
	s_branch .LBB0_206

; #define A_GLOAD(KR, VR, CR, JT) { const int s1_ = (JT) * 64; KR = *(const u32x4*)(kp + (size_t)s1_ * ldk); \
;     _Pragma("unroll") for (int i_ = 0; i_ < DVT / 2; ++i_) VR[i_] = *(const u32x4*)(vp + (size_t)(64 * i_) * SEQ + s1_); \
;     if (FOX) { if (tid < 16) { f32x4 t_ = *(const f32x4*)(cbase + s1_ + tid * 4); CR[0] = -t_[0]; CR[1] = -t_[1]; CR[2] = -t_[2]; CR[3] = -t_[3]; } } }
; template <int DVT, bool FOX> ...
;     ...
;     if (j >= 2) A_GLOAD(kr0, vr0, cr0, j - 2);
.LBB0_223:
	s_add_i32 s96, s86, 64
	s_lshl_b64 s[88:89], s[96:97], 11
	v_lshl_add_u64 v[34:35], v[118:119], 0, s[88:89]
	v_lshl_add_u64 v[36:37], s[96:97], 1, v[120:121]
	global_load_dwordx4 v[82:85], v[34:35], off
	global_load_dwordx4 v[86:89], v[36:37], off
	s_and_saveexec_b64 s[88:89], s[8:9]
	s_cbranch_execz .LBB0_225
	v_lshl_add_u64 v[34:35], s[96:97], 2, v[124:125]
	global_load_dwordx4 v[90:93], v[34:35], off

; #define A_GLOAD(KR, VR, CR, JT) { const int s1_ = (JT) * 64; KR = *(const u32x4*)(kp + (size_t)s1_ * ldk); \
;     _Pragma("unroll") for (int i_ = 0; i_ < DVT / 2; ++i_) VR[i_] = *(const u32x4*)(vp + (size_t)(64 * i_) * SEQ + s1_); \
;     if (FOX) { if (tid < 16) { f32x4 t_ = *(const f32x4*)(cbase + s1_ + tid * 4); CR[0] = -t_[0]; CR[1] = -t_[1]; CR[2] = -t_[2]; CR[3] = -t_[3]; } } }
; template <int DVT, bool FOX> ...
;     ...
;     if (j >= 2) A_GLOAD(kr1, vr1, cr1, j - 2);
.LBB0_232:
	s_mov_b32 s87, s97
	s_lshl_b64 s[88:89], s[86:87], 11
	v_lshl_add_u64 v[34:35], v[118:119], 0, s[88:89]
	v_lshl_add_u64 v[36:37], s[86:87], 1, v[120:121]
	global_load_dwordx4 v[94:97], v[34:35], off
	global_load_dwordx4 v[102:105], v[36:37], off
	s_and_saveexec_b64 s[88:89], s[8:9]
	s_cbranch_execz .LBB0_234
	v_lshl_add_u64 v[34:35], s[86:87], 2, v[124:125]
	global_load_dwordx4 v[98:101], v[34:35], off

; DI int tid_l() { int t = threadIdx.x; asm volatile("" : "+v"(t)); return t; }
; #define A_GLOAD(KR, VR, CR, JT) { const int s1_ = (JT) * 64; KR = *(const u32x4*)(kp + (size_t)s1_ * ldk); \
;     _Pragma("unroll") for (int i_ = 0; i_ < DVT / 2; ++i_) VR[i_] = *(const u32x4*)(vp + (size_t)(64 * i_) * SEQ + s1_); \
;     if (FOX) { if (tid < 16) { f32x4 t_ = *(const f32x4*)(cbase + s1_ + tid * 4); CR[0] = -t_[0]; CR[1] = -t_[1]; CR[2] = -t_[2]; CR[3] = -t_[3]; } } }
; #define A_LSTORE(KR, VR, CR, STG) { char* kb_ = lds + (STG) * STAGE; char* vb_ = kb_ + 64 * LROW; char* cb_ = vb_ + VB; \
;     *(u32x4*)(kb_ + lrow * LROW + lch * 16) = KR; \
;     _Pragma("unroll") for (int i_ = 0; i_ < DVT / 2; ++i_) *(u32x4*)(vb_ + (lrow + 64 * i_) * LROW + lch * 16) = VR[i_]; \
;     if (FOX) { if (tid < 16) *(f32x4*)(cb_ + tid * 16) = CR; } }
; template <int DVT, bool FOX> ...
;     ...
;   const int tid = tid_l(), lane = tid & 63;
;   const int r = lane & 31, hh = lane >> 5;
;   const int lrow = tid >> 3, lch = tid & 7;
;   bf16x8 qf[4];
; #pragma unroll
;   for (int ks = 0; ks < 4; ++ks) qf[ks] = *(const bf16x8*)(qrow + ks * 16 + hh * 8);
; #pragma unroll
;   for (int d = 0; d < DVT; ++d)
; #pragma unroll
;     for (int i = 0; i < 16; ++i) o[d][i] = 0.f;
;   float m = 0.f, l = 0.f;
;   u32x4 kr0, kr1, vr0[DVT / 2], vr1[DVT / 2]; f32x4 cr0 = {0.f, 0.f, 0.f, 0.f}, cr1 = {0.f, 0.f, 0.f, 0.f};
;   const bf16_t* kp = kbase + (size_t)lrow * ldk + lch * 8;
;   const bf16_t* vp = vtbase + (size_t)lrow * SEQ + lch * 8;
;     ...
;   int j = j_hi;
;   A_GLOAD(kr0, vr0, cr0, j);
;   if (j >= 1) A_GLOAD(kr1, vr1, cr1, j - 1);
;   A_LSTORE(kr0, vr0, cr0, 0);
; DI void diff_phase(const Params& p, const int j_even, char* lds) {
;     ...
;     const int bh = blockIdx.x & 7, pp = blockIdx.x >> 3, b = bh >> 2, h = bh & 3;
;     for (int half = 0; half < 2; ++half) {
;       const int qb = half == 0 ? 63 - pp : pp;
;       const int t0 = qb * 256, tq0 = t0 + wave * 32, tq = tq0 + r;
;       const int nkv = (t0 + 256) >> 6, my_last = tq0 >> 6;
;       f32x16 o1[4], o2[4]; float l1, l2;
;       attn_pass<4, false>(bq + (size_t)(b * SEQ + tq) * 512 + h * 128, bk + (size_t)(b * SEQ) * 512 + h * 128, 512,
;                           bvT + (size_t)(bh * 128) * SEQ, nullptr, nkv - 1, my_last, 0, tq, 0.f, o1, l1, lds);
.LBB0_636:
	s_and_b64 s[2:3], s[12:13], exec
	v_readlane_b32 s2, v254, 3
	v_readlane_b32 s3, v254, 4
	s_cselect_b32 s2, s3, s2
	s_lshl_b32 s3, s2, 8
	s_add_i32 s2, s3, s24
	v_add_u32_e32 v160, s2, v179
	v_ashrrev_i32_e32 v161, 31, v160
	v_mov_b32_e32 v5, v192
	v_lshlrev_b64 v[2:3], 10, v[160:161]
	v_lshl_add_u64 v[162:163], s[6:7], 0, v[2:3]
	v_bfe_u32 v4, v5, 5, 1
	v_ashrrev_i32_e32 v2, 3, v5
	v_lshlrev_b32_e32 v0, 4, v4
	v_lshl_add_u64 v[6:7], v[162:163], 0, v[0:1]
	v_ashrrev_i32_e32 v3, 31, v2
	global_load_dwordx4 v[112:115], v[6:7], off
	global_load_dwordx4 v[116:119], v[6:7], off offset:32
	global_load_dwordx4 v[120:123], v[6:7], off offset:64
	global_load_dwordx4 v[124:127], v[6:7], off offset:96
	v_and_b32_e32 v0, 7, v5
	v_lshlrev_b64 v[6:7], 10, v[2:3]
	v_lshl_add_u64 v[6:7], s[8:9], 0, v[6:7]
	v_lshlrev_b32_e32 v0, 4, v0
	v_lshl_add_u64 v[164:165], v[6:7], 0, v[0:1]
	v_lshlrev_b64 v[6:7], 15, v[2:3]
	s_or_b32 s4, s3, 0xc0
	v_lshl_add_u64 v[6:7], s[10:11], 0, v[6:7]
	s_ashr_i32 s5, s4, 31
	v_lshl_add_u64 v[166:167], v[6:7], 0, v[0:1]
	v_subrev_u32_e32 v217, s8, v164
	v_subrev_u32_e32 v222, s10, v166
	v_add_u32_e32 v227, 0x200000, v222
	s_lshl_b64 s[16:17], s[4:5], 10
	v_lshl_add_u64 v[6:7], v[164:165], 0, s[16:17]
	v_lshl_add_u64 v[8:9], s[4:5], 1, v[166:167]
	global_load_dwordx4 v[128:131], v[6:7], off
	global_load_dwordx4 v[132:135], v[8:9], off
	v_add_co_u32_e32 v6, vcc, 0x200000, v8
	s_addk_i32 s3, 0x100
	s_nop 0
	v_addc_co_u32_e32 v7, vcc, 0, v9, vcc
	global_load_dwordx4 v[136:139], v[6:7], off
	s_ashr_i32 s3, s3, 6
	s_cmp_gt_i32 s3, 1
	v_mov_b32_e32 v168, 0
	s_cselect_b64 s[18:19], -1, 0
	s_cmp_lt_i32 s3, 2
	v_mov_b32_e32 v144, 0
	v_mov_b32_e32 v145, 0
	v_mov_b32_e32 v146, 0
	v_mov_b32_e32 v147, 0
	v_mov_b32_e32 v148, 0
	v_mov_b32_e32 v149, 0
	v_mov_b32_e32 v150, 0
	v_mov_b32_e32 v151, 0
	s_cbranch_scc1 .LBB0_638
	s_sub_i32 s96, s4, 64
	s_lshl_b64 s[14:15], s[96:97], 10
	v_lshl_add_u64 v[6:7], v[164:165], 0, s[14:15]
	v_lshl_add_u64 v[8:9], s[96:97], 1, v[166:167]
	global_load_dwordx4 v[140:143], v[6:7], off
	global_load_dwordx4 v[144:147], v[8:9], off
	v_add_co_u32_e32 v6, vcc, 0x200000, v8
	s_nop 1
	v_addc_co_u32_e32 v7, vcc, 0, v9, vcc
	global_load_dwordx4 v[148:151], v[6:7], off

; #define A_GLOAD(KR, VR, CR, JT) { const int s1_ = (JT) * 64; KR = *(const u32x4*)(kp + (size_t)s1_ * ldk); \
;     _Pragma("unroll") for (int i_ = 0; i_ < DVT / 2; ++i_) VR[i_] = *(const u32x4*)(vp + (size_t)(64 * i_) * SEQ + s1_); \
;     if (FOX) { if (tid < 16) { f32x4 t_ = *(const f32x4*)(cbase + s1_ + tid * 4); CR[0] = -t_[0]; CR[1] = -t_[1]; CR[2] = -t_[2]; CR[3] = -t_[3]; } } }
; template <int DVT, bool FOX> ...
;     ...
;     if (j >= 2) A_GLOAD(kr0, vr0, cr0, j - 2);
.LBB0_640:
	s_add_i32 s3, s2, 1
	s_cmp_lt_i32 s3, 2
	s_cbranch_scc1 .LBB0_642
	s_add_i32 s96, s20, 64
	s_lshl_b64 s[22:23], s[96:97], 10
	s_add_u32 s98, s8, s22
	s_addc_u32 s99, s9, s23
	s_lshl_b32 s100, s96, 1
	s_add_u32 s100, s10, s100
	s_addc_u32 s101, s11, 0
	global_load_dwordx4 v[128:131], v217, s[98:99]
	global_load_dwordx4 v[132:135], v222, s[100:101]
	global_load_dwordx4 v[136:139], v227, s[100:101]

; #define A_GLOAD(KR, VR, CR, JT) { const int s1_ = (JT) * 64; KR = *(const u32x4*)(kp + (size_t)s1_ * ldk); \
;     _Pragma("unroll") for (int i_ = 0; i_ < DVT / 2; ++i_) VR[i_] = *(const u32x4*)(vp + (size_t)(64 * i_) * SEQ + s1_); \
;     if (FOX) { if (tid < 16) { f32x4 t_ = *(const f32x4*)(cbase + s1_ + tid * 4); CR[0] = -t_[0]; CR[1] = -t_[1]; CR[2] = -t_[2]; CR[3] = -t_[3]; } } }
; template <int DVT, bool FOX> ...
;     ...
;     if (j >= 2) A_GLOAD(kr1, vr1, cr1, j - 2);
.LBB0_649:
	s_mov_b32 s21, s97
	s_lshl_b64 s[22:23], s[20:21], 10
	s_add_u32 s98, s8, s22
	s_addc_u32 s99, s9, s23
	s_lshl_b32 s100, s20, 1
	s_add_u32 s100, s10, s100
	s_addc_u32 s101, s11, 0
	global_load_dwordx4 v[140:143], v217, s[98:99]
	global_load_dwordx4 v[144:147], v222, s[100:101]
	global_load_dwordx4 v[148:151], v227, s[100:101]
	s_cmp_gt_i32 s2, s25
	s_cbranch_scc1 .LBB0_648

; DI unsigned pk2(float lo, float hi) { f32x2 v = {lo, hi}; bf16x2v b = __builtin_convertvector(v, bf16x2v); return __builtin_bit_cast(unsigned, b); }
; DI int tid_l() { int t = threadIdx.x; asm volatile("" : "+v"(t)); return t; }
; #define A_GLOAD(KR, VR, CR, JT) { const int s1_ = (JT) * 64; KR = *(const u32x4*)(kp + (size_t)s1_ * ldk); \
;     _Pragma("unroll") for (int i_ = 0; i_ < DVT / 2; ++i_) VR[i_] = *(const u32x4*)(vp + (size_t)(64 * i_) * SEQ + s1_); \
;     if (FOX) { if (tid < 16) { f32x4 t_ = *(const f32x4*)(cbase + s1_ + tid * 4); CR[0] = -t_[0]; CR[1] = -t_[1]; CR[2] = -t_[2]; CR[3] = -t_[3]; } } }
; template <int DVT, bool FOX> ...
;     ...
;   const int tid = tid_l(), lane = tid & 63;
;   const int r = lane & 31, hh = lane >> 5;
;   const int lrow = tid >> 3, lch = tid & 7;
;   bf16x8 qf[4];
; #pragma unroll
;   for (int ks = 0; ks < 4; ++ks) qf[ks] = *(const bf16x8*)(qrow + ks * 16 + hh * 8);
; #pragma unroll
;   for (int d = 0; d < DVT; ++d)
; #pragma unroll
;     for (int i = 0; i < 16; ++i) o[d][i] = 0.f;
;   float m = 0.f, l = 0.f;
;   u32x4 kr0, kr1, vr0[DVT / 2], vr1[DVT / 2]; f32x4 cr0 = {0.f, 0.f, 0.f, 0.f}, cr1 = {0.f, 0.f, 0.f, 0.f};
;   const bf16_t* kp = kbase + (size_t)lrow * ldk + lch * 8;
;   const bf16_t* vp = vtbase + (size_t)lrow * SEQ + lch * 8;
;     ...
;   int j = j_hi;
;   A_GLOAD(kr0, vr0, cr0, j);
;   if (j >= 1) A_GLOAD(kr1, vr1, cr1, j - 1);
; DI void diff_phase(const Params& p, const int j_even, char* lds) {
;     ...
;       const float i1 = 1.f / l1;
;       unsigned* o1s = (unsigned*)(lds + DIFF_STASH_OFF) + tid;
; #pragma unroll
;       for (int d = 0; d < 4; ++d)
; #pragma unroll
;         for (int i = 0; i < 8; ++i) o1s[(d * 8 + i) * 512] = pk2(o1[d][2 * i] * i1, o1[d][2 * i + 1] * i1);
;       attn_pass<4, false>(bq + (size_t)(b * SEQ + tq) * 512 + h * 128 + 64, bk + (size_t)(b * SEQ) * 512 + h * 128 + 64, 512,
.LBB0_653:
.LBB0_654:
	v_mov_b32_e32 v2, v0
	s_nop 1
	v_permlane32_swap_b32_e32 v0, v2
	v_add_f32_e32 v0, v0, v2
	v_div_scale_f32 v2, s[2:3], v0, v0, 1.0
	v_rcp_f32_e32 v3, v2
	s_barrier
	v_fma_f32 v4, -v2, v3, 1.0
	v_fmac_f32_e32 v3, v4, v3
	v_div_scale_f32 v4, vcc, 1.0, v0, 1.0
	v_mul_f32_e32 v5, v4, v3
	v_fma_f32 v6, -v2, v5, v4
	v_fmac_f32_e32 v5, v6, v3
	v_fma_f32 v2, -v2, v5, v4
	v_div_fmas_f32 v2, v2, v3, v5
	v_div_fixup_f32 v0, v2, v0, 1.0
	v_pk_mul_f32 v[2:3], v[64:65], v[0:1] op_sel_hi:[1,0]
	v_mov_b32_e32 v5, v192
	v_cvt_pk_bf16_f32 v4, v2, v3
	v_pk_mul_f32 v[2:3], v[66:67], v[0:1] op_sel_hi:[1,0]
	v_mov_b32_e32 v166, 0
	v_cvt_pk_bf16_f32 v2, v2, v3
	ds_write2st64_b32 v180, v4, v2 offset0:218 offset1:226
	v_pk_mul_f32 v[2:3], v[68:69], v[0:1] op_sel_hi:[1,0]
	s_waitcnt vmcnt(1)
	v_mov_b32_e32 v144, 0
	v_cvt_pk_bf16_f32 v4, v2, v3
	v_pk_mul_f32 v[2:3], v[70:71], v[0:1] op_sel_hi:[1,0]
	v_mov_b32_e32 v145, 0
	v_cvt_pk_bf16_f32 v2, v2, v3
	ds_write2st64_b32 v180, v4, v2 offset0:234 offset1:242
	v_pk_mul_f32 v[2:3], v[72:73], v[0:1] op_sel_hi:[1,0]
	v_mov_b32_e32 v146, 0
	v_cvt_pk_bf16_f32 v2, v2, v3
	ds_write_b32 v180, v2 offset:64000
	v_pk_mul_f32 v[2:3], v[74:75], v[0:1] op_sel_hi:[1,0]
	v_mov_b32_e32 v147, 0
	v_cvt_pk_bf16_f32 v4, v2, v3
	v_pk_mul_f32 v[2:3], v[76:77], v[0:1] op_sel_hi:[1,0]
	s_waitcnt vmcnt(0)
	v_mov_b32_e32 v148, 0
	v_cvt_pk_bf16_f32 v2, v2, v3
	ds_write2st64_b32 v181, v4, v2 offset0:40 offset1:48
	v_pk_mul_f32 v[2:3], v[78:79], v[0:1] op_sel_hi:[1,0]
	v_mov_b32_e32 v149, 0
	v_cvt_pk_bf16_f32 v4, v2, v3
	v_pk_mul_f32 v[2:3], v[48:49], v[0:1] op_sel_hi:[1,0]
	v_mov_b32_e32 v150, 0
	v_cvt_pk_bf16_f32 v2, v2, v3
	ds_write2st64_b32 v181, v4, v2 offset0:56 offset1:64
	v_pk_mul_f32 v[2:3], v[50:51], v[0:1] op_sel_hi:[1,0]
	v_mov_b32_e32 v151, 0
	v_cvt_pk_bf16_f32 v4, v2, v3
	v_pk_mul_f32 v[2:3], v[52:53], v[0:1] op_sel_hi:[1,0]
	s_nop 0
	v_cvt_pk_bf16_f32 v2, v2, v3
	ds_write2st64_b32 v181, v4, v2 offset0:72 offset1:80
	v_pk_mul_f32 v[2:3], v[54:55], v[0:1] op_sel_hi:[1,0]
	s_nop 0
	v_cvt_pk_bf16_f32 v4, v2, v3
	v_pk_mul_f32 v[2:3], v[56:57], v[0:1] op_sel_hi:[1,0]
	s_nop 0
	v_cvt_pk_bf16_f32 v2, v2, v3
	ds_write2st64_b32 v181, v4, v2 offset0:88 offset1:96
	v_pk_mul_f32 v[2:3], v[58:59], v[0:1] op_sel_hi:[1,0]
	s_nop 0
	v_cvt_pk_bf16_f32 v4, v2, v3
	v_pk_mul_f32 v[2:3], v[60:61], v[0:1] op_sel_hi:[1,0]
	s_nop 0
	v_cvt_pk_bf16_f32 v2, v2, v3
	ds_write2st64_b32 v181, v4, v2 offset0:104 offset1:112
	v_pk_mul_f32 v[2:3], v[62:63], v[0:1] op_sel_hi:[1,0]
	s_nop 0
	v_cvt_pk_bf16_f32 v4, v2, v3
	v_pk_mul_f32 v[2:3], v[32:33], v[0:1] op_sel_hi:[1,0]
	s_nop 0
	v_cvt_pk_bf16_f32 v2, v2, v3
	ds_write2st64_b32 v181, v4, v2 offset0:120 offset1:128
	v_pk_mul_f32 v[2:3], v[34:35], v[0:1] op_sel_hi:[1,0]
	s_nop 0
	v_cvt_pk_bf16_f32 v4, v2, v3
	v_pk_mul_f32 v[2:3], v[36:37], v[0:1] op_sel_hi:[1,0]
	s_nop 0
	v_cvt_pk_bf16_f32 v2, v2, v3
	ds_write2st64_b32 v181, v4, v2 offset0:136 offset1:144
	v_pk_mul_f32 v[2:3], v[38:39], v[0:1] op_sel_hi:[1,0]
	s_nop 0
	v_cvt_pk_bf16_f32 v4, v2, v3
	v_pk_mul_f32 v[2:3], v[40:41], v[0:1] op_sel_hi:[1,0]
	s_nop 0
	v_cvt_pk_bf16_f32 v2, v2, v3
	ds_write2st64_b32 v181, v4, v2 offset0:152 offset1:160
	v_pk_mul_f32 v[2:3], v[42:43], v[0:1] op_sel_hi:[1,0]
	s_nop 0
	v_cvt_pk_bf16_f32 v4, v2, v3
	v_pk_mul_f32 v[2:3], v[44:45], v[0:1] op_sel_hi:[1,0]
	s_nop 0
	v_cvt_pk_bf16_f32 v2, v2, v3
	ds_write2st64_b32 v181, v4, v2 offset0:168 offset1:176
	v_pk_mul_f32 v[2:3], v[46:47], v[0:1] op_sel_hi:[1,0]
	s_nop 0
	v_cvt_pk_bf16_f32 v4, v2, v3
	v_pk_mul_f32 v[2:3], v[16:17], v[0:1] op_sel_hi:[1,0]
	s_nop 0
	v_cvt_pk_bf16_f32 v2, v2, v3
	ds_write2st64_b32 v181, v4, v2 offset0:184 offset1:192
	v_pk_mul_f32 v[2:3], v[18:19], v[0:1] op_sel_hi:[1,0]
	s_nop 0
	v_cvt_pk_bf16_f32 v4, v2, v3
	v_pk_mul_f32 v[2:3], v[20:21], v[0:1] op_sel_hi:[1,0]
	s_nop 0
	v_cvt_pk_bf16_f32 v2, v2, v3
	ds_write2st64_b32 v181, v4, v2 offset0:200 offset1:208
	v_pk_mul_f32 v[2:3], v[22:23], v[0:1] op_sel_hi:[1,0]
	s_nop 0
	v_cvt_pk_bf16_f32 v4, v2, v3
	v_pk_mul_f32 v[2:3], v[24:25], v[0:1] op_sel_hi:[1,0]
	s_nop 0
	v_cvt_pk_bf16_f32 v2, v2, v3
	ds_write2st64_b32 v181, v4, v2 offset0:216 offset1:224
	v_pk_mul_f32 v[2:3], v[26:27], v[0:1] op_sel_hi:[1,0]
	s_nop 0
	v_cvt_pk_bf16_f32 v4, v2, v3
	v_pk_mul_f32 v[2:3], v[28:29], v[0:1] op_sel_hi:[1,0]
	s_nop 0
	v_cvt_pk_bf16_f32 v2, v2, v3
	ds_write2st64_b32 v181, v4, v2 offset0:232 offset1:240
	v_pk_mul_f32 v[2:3], v[30:31], v[0:1] op_sel_hi:[1,0]
	s_nop 0
	v_cvt_pk_bf16_f32 v0, v2, v3
	ds_write_b32 v181, v0 offset:63488
	s_nop 0
	v_bfe_u32 v4, v5, 5, 1
	v_ashrrev_i32_e32 v2, 3, v5
	v_lshlrev_b32_e32 v0, 4, v4
	v_lshl_add_u64 v[6:7], v[162:163], 0, v[0:1]
	v_ashrrev_i32_e32 v3, 31, v2
	global_load_dwordx4 v[112:115], v[6:7], off offset:128
	global_load_dwordx4 v[116:119], v[6:7], off offset:160
	global_load_dwordx4 v[120:123], v[6:7], off offset:192
	global_load_dwordx4 v[124:127], v[6:7], off offset:224
	v_and_b32_e32 v0, 7, v5
	v_lshlrev_b64 v[6:7], 10, v[2:3]
	v_lshl_add_u64 v[6:7], s[8:9], 0, v[6:7]
	v_lshlrev_b32_e32 v0, 4, v0
	v_lshl_add_u64 v[162:163], v[6:7], 0, v[0:1]
	v_lshlrev_b64 v[6:7], 15, v[2:3]
	v_lshl_add_u64 v[6:7], s[10:11], 0, v[6:7]
	v_lshl_add_u64 v[164:165], v[6:7], 0, v[0:1]
	v_subrev_u32_e32 v217, s8, v162
	v_subrev_u32_e32 v222, s10, v164
	v_add_u32_e32 v227, 0x200000, v222
	v_lshl_add_u64 v[6:7], v[162:163], 0, s[16:17]
	v_lshl_add_u64 v[8:9], s[4:5], 1, v[164:165]
	global_load_dwordx4 v[128:131], v[6:7], off offset:128
	global_load_dwordx4 v[132:135], v[8:9], off
	v_add_co_u32_e32 v6, vcc, 0x200000, v8
	s_nop 1
	v_addc_co_u32_e32 v7, vcc, 0, v9, vcc
	global_load_dwordx4 v[136:139], v[6:7], off
	s_andn2_b64 vcc, exec, s[18:19]
	s_cbranch_vccnz .LBB0_656
	s_sub_i32 s96, s4, 64
	s_lshl_b64 s[2:3], s[96:97], 10
	v_lshl_add_u64 v[6:7], v[162:163], 0, s[2:3]
	v_lshl_add_u64 v[8:9], s[96:97], 1, v[164:165]
	global_load_dwordx4 v[140:143], v[6:7], off offset:128
	global_load_dwordx4 v[144:147], v[8:9], off
	v_add_co_u32_e32 v6, vcc, 0x200000, v8
	s_nop 1
	v_addc_co_u32_e32 v7, vcc, 0, v9, vcc
	global_load_dwordx4 v[148:151], v[6:7], off

; #define A_GLOAD(KR, VR, CR, JT) { const int s1_ = (JT) * 64; KR = *(const u32x4*)(kp + (size_t)s1_ * ldk); \
;     _Pragma("unroll") for (int i_ = 0; i_ < DVT / 2; ++i_) VR[i_] = *(const u32x4*)(vp + (size_t)(64 * i_) * SEQ + s1_); \
;     if (FOX) { if (tid < 16) { f32x4 t_ = *(const f32x4*)(cbase + s1_ + tid * 4); CR[0] = -t_[0]; CR[1] = -t_[1]; CR[2] = -t_[2]; CR[3] = -t_[3]; } } }
; template <int DVT, bool FOX> ...
;     ...
;     if (j >= 2) A_GLOAD(kr0, vr0, cr0, j - 2);
.LBB0_658:
	s_add_i32 s2, s27, 1
	s_cmp_lt_i32 s2, 2
	s_cbranch_scc1 .LBB0_660
	s_add_i32 s96, s14, 64
	s_lshl_b64 s[4:5], s[96:97], 10
	s_add_u32 s98, s8, s4
	s_addc_u32 s99, s9, s5
	s_lshl_b32 s100, s96, 1
	s_add_u32 s100, s10, s100
	s_addc_u32 s101, s11, 0
	global_load_dwordx4 v[128:131], v217, s[98:99] offset:128
	global_load_dwordx4 v[132:135], v222, s[100:101]
	global_load_dwordx4 v[136:139], v227, s[100:101]

; #define A_GLOAD(KR, VR, CR, JT) { const int s1_ = (JT) * 64; KR = *(const u32x4*)(kp + (size_t)s1_ * ldk); \
;     _Pragma("unroll") for (int i_ = 0; i_ < DVT / 2; ++i_) VR[i_] = *(const u32x4*)(vp + (size_t)(64 * i_) * SEQ + s1_); \
;     if (FOX) { if (tid < 16) { f32x4 t_ = *(const f32x4*)(cbase + s1_ + tid * 4); CR[0] = -t_[0]; CR[1] = -t_[1]; CR[2] = -t_[2]; CR[3] = -t_[3]; } } }
; template <int DVT, bool FOX> ...
;     ...
;     if (j >= 2) A_GLOAD(kr1, vr1, cr1, j - 2);
.LBB0_667:
	s_mov_b32 s15, s97
	s_lshl_b64 s[4:5], s[14:15], 10
	s_add_u32 s98, s8, s4
	s_addc_u32 s99, s9, s5
	s_lshl_b32 s100, s14, 1
	s_add_u32 s100, s10, s100
	s_addc_u32 s101, s11, 0
	global_load_dwordx4 v[140:143], v217, s[98:99] offset:128
	global_load_dwordx4 v[144:147], v222, s[100:101]
	global_load_dwordx4 v[148:151], v227, s[100:101]
	s_cmp_gt_i32 s27, s25
	s_cbranch_scc1 .LBB0_666
